# loop-head alignment extended to the P3 K-loop and the three memory-attention tile loops
# baseline (speedup 1.0000x reference)
; #define LAS __attribute__((address_space(3)))
; DI void unit_memattn(int u, const bf16* __restrict__ MQ, const bf16* __restrict__ MK, const bf16* __restrict__ MV, const bf16* __restrict__ G, bf16* __restrict__ MIX, const bf16* __restrict__ CB, const bf16* __restrict__ U, const float* __restrict__ convw, ...
;     ...
; #pragma unroll
;     for (int i = 0; i < 4; ++i) { const int id = tid + NT * i, j = id >> 3, ch = id & 7;
;         *(LAS v4u*)(lds + ATT_K + j * KP + ch * 16) = fk[i]; *(LAS v4u*)(lds + ATT_V + j * KP + ch * 16) = fv[i]; }
;     const int qq = lane & 31, hh = lane >> 5;
;     const int row = b * SEQ + qb * 256 + 32 * wave + qq;
;     bf16x8 qf[4];
; #pragma unroll
;     for (int st = 0; st < 4; ++st) qf[st] = *(const bf16x8*)(MQ + (size_t)row * 256 + hm * 64 + 16 * st + 8 * hh);
;     __syncthreads();
;     f32x16 o0, o1;
; #pragma unroll
;     for (int i = 0; i < 16; ++i) { o0[i] = 0.f; o1[i] = 0.f; }
;     float m = NEG, l = 0.f;
;     for (int a = 0; a < 4; ++a) attn_tile64(lds + ATT_K, lds + ATT_V, 64 * a, qf, lane, o0, o1, m, l);
.LBB0_530:
	s_or_b64 exec, exec, s[14:15]
	s_lshl_b32 s2, s12, 13
	s_add_i32 s3, s13, s22
	v_and_b32_e32 v133, 31, v153
	s_add_i32 s3, s3, s2
	s_waitcnt vmcnt(2)
	v_or_b32_e32 v36, s3, v133
	v_ashrrev_i32_e32 v37, 31, v36
	v_ashrrev_i32_e32 v38, 5, v153
	v_lshlrev_b64 v[36:37], 9, v[36:37]
	v_lshl_add_u64 v[36:37], s[60:61], 0, v[36:37]
	v_lshlrev_b32_e32 v150, 3, v38
	v_lshl_add_u64 v[36:37], v[36:37], 0, s[4:5]
	v_ashrrev_i32_e32 v151, 31, v150
	v_lshl_add_u64 v[36:37], v[150:151], 1, v[36:37]
	global_load_dwordx4 v[84:87], v[36:37], off
	global_load_dwordx4 v[88:91], v[36:37], off offset:32
	global_load_dwordx4 v[92:95], v[36:37], off offset:64
	global_load_dwordx4 v[96:99], v[36:37], off offset:96
	v_lshlrev_b32_e32 v2, 4, v152
	v_and_b32_e32 v2, 0x70, v2
	v_add_u32_e32 v2, 0, v2
	v_mad_u64_u32 v[36:37], s[2:3], v142, s31, v[2:3]
	ds_write_b128 v36, v[4:7]
	ds_write_b128 v36, v[8:11] offset:55296
	v_mad_u64_u32 v[4:5], s[2:3], v144, s31, v[2:3]
	ds_write_b128 v4, v[12:15]
	ds_write_b128 v4, v[16:19] offset:55296
	v_mad_u64_u32 v[4:5], s[2:3], v146, s31, v[2:3]
	ds_write_b128 v4, v[20:23]
	ds_write_b128 v4, v[24:27] offset:55296
	v_mad_u64_u32 v[4:5], s[2:3], v148, s31, v[2:3]
	ds_write_b128 v4, v[28:31]
	s_waitcnt vmcnt(5)
	ds_write_b128 v4, v[32:35] offset:55296
	v_lshlrev_b32_e32 v2, 4, v38
	v_bfe_u32 v4, v153, 2, 2
	v_lshlrev_b32_e32 v5, 1, v153
	v_mul_u32_u24_e32 v7, 0x90, v133
	v_and_b32_e32 v5, 32, v5
	v_lshlrev_b32_e32 v6, 3, v153
	v_add3_u32 v149, v7, v2, 0
	v_mul_lo_u32 v2, v38, s34
	v_mul_u32_u24_e32 v4, 0x90, v4
	v_and_b32_e32 v6, 24, v6
	v_add3_u32 v2, v2, v4, v5
	v_mov_b32_e32 v16, v3
	v_mov_b32_e32 v17, v3
	v_add3_u32 v151, v2, v6, 0
	v_mov_b32_e32 v2, v3
	v_mov_b32_e32 v4, v3
	v_mov_b32_e32 v5, v3
	v_mov_b32_e32 v6, v3
	v_mov_b32_e32 v7, v3
	v_mov_b32_e32 v8, v3
	v_mov_b32_e32 v9, v3
	v_mov_b32_e32 v10, v3
	v_mov_b32_e32 v11, v3
	v_mov_b32_e32 v12, v3
	v_mov_b32_e32 v13, v3
	v_mov_b32_e32 v14, v3
	v_mov_b32_e32 v15, v3
	v_mov_b64_e32 v[34:35], v[16:17]
	v_mov_b64_e32 v[32:33], v[14:15]
	v_mov_b64_e32 v[30:31], v[12:13]
	v_mov_b64_e32 v[28:29], v[10:11]
	v_mov_b64_e32 v[26:27], v[8:9]
	v_mov_b64_e32 v[24:25], v[6:7]
	v_mov_b64_e32 v[22:23], v[4:5]
	v_mov_b64_e32 v[20:21], v[2:3]
	v_mov_b64_e32 v[18:19], v[16:17]
	s_mov_b32 s2, 0
	v_mov_b32_e32 v155, 0xf149f2ca
	v_mov_b32_e32 v154, 0
	v_mov_b64_e32 v[16:17], v[14:15]
	v_mov_b64_e32 v[14:15], v[12:13]
	v_mov_b64_e32 v[12:13], v[10:11]
	v_mov_b64_e32 v[10:11], v[8:9]
	v_mov_b64_e32 v[8:9], v[6:7]
	v_mov_b64_e32 v[6:7], v[4:5]
	v_mov_b64_e32 v[4:5], v[2:3]
	s_waitcnt lgkmcnt(0)
	s_barrier
	.p2align 6

; #define LAS __attribute__((address_space(3)))
; DI void unit_memattn(int u, const bf16* __restrict__ MQ, const bf16* __restrict__ MK, const bf16* __restrict__ MV, const bf16* __restrict__ G, bf16* __restrict__ MIX, const bf16* __restrict__ CB, const bf16* __restrict__ U, const float* __restrict__ convw, ...
;     ...
; #pragma unroll
;     for (int i = 0; i < 4; ++i) { const int id = tid + NT * i, j = id >> 3, ch = id & 7;
;         *(LAS v4u*)(lds + ATT_K + j * KP + ch * 16) = fk[i]; *(LAS v4u*)(lds + ATT_V + j * KP + ch * 16) = fv[i]; }
;     const int qq = lane & 31, hh = lane >> 5;
;     const int row = b * SEQ + qb * 256 + 32 * wave + qq;
;     bf16x8 qf[4];
; #pragma unroll
;     for (int st = 0; st < 4; ++st) qf[st] = *(const bf16x8*)(MQ + (size_t)row * 256 + hm * 64 + 16 * st + 8 * hh);
;     __syncthreads();
;     f32x16 o0, o1;
; #pragma unroll
;     for (int i = 0; i < 16; ++i) { o0[i] = 0.f; o1[i] = 0.f; }
;     float m = NEG, l = 0.f;
;     for (int a = 0; a < 4; ++a) attn_tile64(lds + ATT_K, lds + ATT_V, 64 * a, qf, lane, o0, o1, m, l);
.LBB0_675:
	s_or_b64 exec, exec, s[12:13]
	s_lshl_b32 s0, s33, 5
	s_lshl_b32 s1, s10, 13
	s_add_i32 s2, s11, s0
	v_and_b32_e32 v131, 31, v150
	s_add_i32 s2, s2, s1
	s_waitcnt vmcnt(2)
	v_or_b32_e32 v34, s2, v131
	v_ashrrev_i32_e32 v35, 31, v34
	s_waitcnt vmcnt(1)
	v_ashrrev_i32_e32 v38, 5, v150
	v_lshlrev_b64 v[34:35], 9, v[34:35]
	s_mov_b32 s9, 0
	v_lshl_add_u64 v[34:35], s[60:61], 0, v[34:35]
	v_lshlrev_b32_e32 v148, 3, v38
	v_lshl_add_u64 v[34:35], v[34:35], 0, s[8:9]
	v_ashrrev_i32_e32 v149, 31, v148
	v_lshl_add_u64 v[34:35], v[148:149], 1, v[34:35]
	global_load_dwordx4 v[82:85], v[34:35], off
	global_load_dwordx4 v[86:89], v[34:35], off offset:32
	global_load_dwordx4 v[90:93], v[34:35], off offset:64
	global_load_dwordx4 v[94:97], v[34:35], off offset:96
	v_lshlrev_b32_e32 v34, 4, v1
	v_and_b32_e32 v34, 0x70, v34
	v_add_u32_e32 v34, 0, v34
	s_movk_i32 s1, 0x90
	v_mad_u64_u32 v[36:37], s[2:3], v140, s1, v[34:35]
	ds_write_b128 v36, v[2:5]
	ds_write_b128 v36, v[6:9] offset:55296
	v_mad_u64_u32 v[2:3], s[2:3], v142, s1, v[34:35]
	ds_write_b128 v2, v[10:13]
	ds_write_b128 v2, v[14:17] offset:55296
	v_mad_u64_u32 v[2:3], s[2:3], v144, s1, v[34:35]
	ds_write_b128 v2, v[18:21]
	ds_write_b128 v2, v[22:25] offset:55296
	v_mad_u64_u32 v[2:3], s[2:3], v146, s1, v[34:35]
	ds_write_b128 v2, v[26:29]
	ds_write_b128 v2, v[30:33] offset:55296
	v_lshlrev_b32_e32 v2, 4, v38
	v_bfe_u32 v3, v150, 2, 2
	v_lshlrev_b32_e32 v4, 1, v150
	v_mul_u32_u24_e32 v6, 0x90, v131
	s_movk_i32 s1, 0x240
	v_and_b32_e32 v4, 32, v4
	v_lshlrev_b32_e32 v5, 3, v150
	v_add3_u32 v147, v6, v2, 0
	v_mul_lo_u32 v2, v38, s1
	v_mul_u32_u24_e32 v3, 0x90, v3
	v_and_b32_e32 v5, 24, v5
	v_add3_u32 v2, v2, v3, v4
	v_add3_u32 v149, v2, v5, 0
	v_mov_b32_e32 v2, 0
	v_mov_b32_e32 v16, v2
	v_mov_b32_e32 v17, v2
	v_mov_b32_e32 v3, v2
	v_mov_b32_e32 v4, v2
	v_mov_b32_e32 v5, v2
	v_mov_b32_e32 v6, v2
	v_mov_b32_e32 v7, v2
	v_mov_b32_e32 v8, v2
	v_mov_b32_e32 v9, v2
	v_mov_b32_e32 v10, v2
	v_mov_b32_e32 v11, v2
	v_mov_b32_e32 v12, v2
	v_mov_b32_e32 v13, v2
	v_mov_b32_e32 v14, v2
	v_mov_b32_e32 v15, v2
	v_mov_b64_e32 v[32:33], v[16:17]
	v_mov_b32_e32 v153, 0xf149f2ca
	v_mov_b64_e32 v[30:31], v[14:15]
	v_mov_b64_e32 v[28:29], v[12:13]
	v_mov_b64_e32 v[26:27], v[10:11]
	v_mov_b64_e32 v[24:25], v[8:9]
	v_mov_b64_e32 v[22:23], v[6:7]
	v_mov_b64_e32 v[20:21], v[4:5]
	v_mov_b64_e32 v[18:19], v[2:3]
	v_mov_b32_e32 v151, v2
	s_waitcnt lgkmcnt(0)
	s_barrier
	.p2align 6

; #define LAS __attribute__((address_space(3)))
; DI void unit_memattn(int u, const bf16* __restrict__ MQ, const bf16* __restrict__ MK, const bf16* __restrict__ MV, const bf16* __restrict__ G, bf16* __restrict__ MIX, const bf16* __restrict__ CB, const bf16* __restrict__ U, const float* __restrict__ convw, ...
;     ...
; #pragma unroll
;     for (int i = 0; i < 4; ++i) { const int id = tid + NT * i, j = id >> 3, ch = id & 7;
;         *(LAS v4u*)(lds + ATT_K + j * KP + ch * 16) = fk[i]; *(LAS v4u*)(lds + ATT_V + j * KP + ch * 16) = fv[i]; }
;     const int qq = lane & 31, hh = lane >> 5;
;     const int row = b * SEQ + qb * 256 + 32 * wave + qq;
;     bf16x8 qf[4];
; #pragma unroll
;     for (int st = 0; st < 4; ++st) qf[st] = *(const bf16x8*)(MQ + (size_t)row * 256 + hm * 64 + 16 * st + 8 * hh);
;     __syncthreads();
;     f32x16 o0, o1;
; #pragma unroll
;     for (int i = 0; i < 16; ++i) { o0[i] = 0.f; o1[i] = 0.f; }
;     float m = NEG, l = 0.f;
;     for (int a = 0; a < 4; ++a) attn_tile64(lds + ATT_K, lds + ATT_V, 64 * a, qf, lane, o0, o1, m, l);
.LBB0_823:
	s_or_b64 exec, exec, s[16:17]
	s_lshl_b32 s0, s14, 13
	s_add_i32 s1, s15, s62
	v_and_b32_e32 v133, 31, v154
	s_add_i32 s1, s1, s0
	s_waitcnt vmcnt(2)
	v_or_b32_e32 v36, s1, v133
	v_ashrrev_i32_e32 v37, 31, v36
	v_ashrrev_i32_e32 v38, 5, v154
	v_lshlrev_b64 v[36:37], 9, v[36:37]
	v_lshl_add_u64 v[36:37], s[72:73], 0, v[36:37]
	v_lshlrev_b32_e32 v150, 3, v38
	v_lshl_add_u64 v[36:37], v[36:37], 0, s[6:7]
	v_ashrrev_i32_e32 v151, 31, v150
	v_lshl_add_u64 v[36:37], v[150:151], 1, v[36:37]
	global_load_dwordx4 v[84:87], v[36:37], off
	global_load_dwordx4 v[88:91], v[36:37], off offset:32
	global_load_dwordx4 v[92:95], v[36:37], off offset:64
	global_load_dwordx4 v[96:99], v[36:37], off offset:96
	v_lshlrev_b32_e32 v2, 4, v153
	v_and_b32_e32 v2, 0x70, v2
	v_add_u32_e32 v2, 0, v2
	v_mad_u64_u32 v[36:37], s[0:1], v142, s39, v[2:3]
	ds_write_b128 v36, v[4:7]
	ds_write_b128 v36, v[8:11] offset:55296
	v_mad_u64_u32 v[4:5], s[0:1], v144, s39, v[2:3]
	ds_write_b128 v4, v[12:15]
	ds_write_b128 v4, v[16:19] offset:55296
	v_mad_u64_u32 v[4:5], s[0:1], v146, s39, v[2:3]
	ds_write_b128 v4, v[20:23]
	ds_write_b128 v4, v[24:27] offset:55296
	v_mad_u64_u32 v[4:5], s[0:1], v148, s39, v[2:3]
	ds_write_b128 v4, v[28:31]
	s_waitcnt vmcnt(5)
	ds_write_b128 v4, v[32:35] offset:55296
	v_lshlrev_b32_e32 v2, 4, v38
	v_bfe_u32 v4, v154, 2, 2
	v_lshlrev_b32_e32 v5, 1, v154
	v_mul_u32_u24_e32 v7, 0x90, v133
	v_and_b32_e32 v5, 32, v5
	v_lshlrev_b32_e32 v6, 3, v154
	v_add3_u32 v149, v7, v2, 0
	v_mul_lo_u32 v2, v38, s40
	v_mul_u32_u24_e32 v4, 0x90, v4
	v_and_b32_e32 v6, 24, v6
	v_add3_u32 v2, v2, v4, v5
	v_mov_b32_e32 v16, v3
	v_mov_b32_e32 v17, v3
	v_add3_u32 v151, v2, v6, 0
	v_mov_b32_e32 v2, v3
	v_mov_b32_e32 v4, v3
	v_mov_b32_e32 v5, v3
	v_mov_b32_e32 v6, v3
	v_mov_b32_e32 v7, v3
	v_mov_b32_e32 v8, v3
	v_mov_b32_e32 v9, v3
	v_mov_b32_e32 v10, v3
	v_mov_b32_e32 v11, v3
	v_mov_b32_e32 v12, v3
	v_mov_b32_e32 v13, v3
	v_mov_b32_e32 v14, v3
	v_mov_b32_e32 v15, v3
	v_mov_b64_e32 v[34:35], v[16:17]
	v_mov_b64_e32 v[32:33], v[14:15]
	v_mov_b64_e32 v[30:31], v[12:13]
	v_mov_b64_e32 v[28:29], v[10:11]
	v_mov_b64_e32 v[26:27], v[8:9]
	v_mov_b64_e32 v[24:25], v[6:7]
	v_mov_b64_e32 v[22:23], v[4:5]
	v_mov_b64_e32 v[20:21], v[2:3]
	v_mov_b64_e32 v[18:19], v[16:17]
	s_mov_b32 s0, 0
	v_mov_b32_e32 v156, 0xf149f2ca
	v_mov_b32_e32 v155, 0
	v_mov_b64_e32 v[16:17], v[14:15]
	v_mov_b64_e32 v[14:15], v[12:13]
	v_mov_b64_e32 v[12:13], v[10:11]
	v_mov_b64_e32 v[10:11], v[8:9]
	v_mov_b64_e32 v[8:9], v[6:7]
	v_mov_b64_e32 v[6:7], v[4:5]
	v_mov_b64_e32 v[4:5], v[2:3]
	s_waitcnt lgkmcnt(0)
	s_barrier
	.p2align 6

; #define PG8_STAGE(bufoff, gbase, voff) do { _Pragma("unroll") for (int _i = 0; _i < 2; ++_i) \
;         __builtin_amdgcn_global_load_lds((const unsigned*)((const char*)(gbase) + (voff)[_i]), (PG8_LAS unsigned*)(lds + (bufoff) + ldsw + _i * 8192), 16, 0, 0); } while (0)
; #define PG8_WAIT_V(n) asm volatile("s_waitcnt vmcnt(" #n ")" ::: "memory")
; #define PG8_BAR __builtin_amdgcn_s_barrier()
; template <class Epi, class Sched, bool ALIGN_EPI = false, bool SP2 = false, bool PRE = false>
; __device__ __forceinline__ void gemm_phase(PG8_LAS unsigned char* lds, const Gemm g, const Sched& S, const Epi& E, const f32x4 (*pre)[2][4][2] = nullptr) {
;     const int tid = threadIdx.x, wid = __builtin_amdgcn_readfirstlane(tid >> 6), lane = tid & 63, wr = wid >> 2, wc = wid & 3, fr = lane & 15, fq = lane >> 4;
;     const int K = g.K, nt = K / BK;
;     unsigned voffA[2], voffB[2];
; #pragma unroll
;     for (int i = 0; i < 2; ++i) { int R, C; stage_rc(tid * 16 + i * 8192, R, C); const int Rb = Epi::PERM ? ((R & ~31) + perm32(R & 31)) : R;
;         voffA[i] = (unsigned)(R * K + C) * 2u; voffB[i] = (unsigned)(Rb * K + C) * 2u; }
;     const size_t kstep = (size_t)(BK * 2);
;     const size_t hstep = (size_t)HALF * K * 2;
;     const size_t tstep = 2 * hstep;
;     const unsigned ldsw = (unsigned)wid * 1024u;
;     const int aoff = lds_byte(wr * 64 + fr, fq * 8), boff = lds_byte(wc * 32 + fr, fq * 8);
;     ...
;         PG8_STAGE(PG8_SB(0, 0), cB, voffB); PG8_STAGE(PG8_SB(0, 1), cB + hstep, voffB); PG8_STAGE(PG8_SA(0, 0), cA, voffA); PG8_STAGE(PG8_SA(0, 1), cA + hstep, voffA);
;         if (wr == 1) PG8_BAR;
;         PG8_WAIT_V(2); PG8_BAR;
;         PG8_STAGE(PG8_SB(1, 0), cB + kstep, voffB); PG8_STAGE(PG8_SA(1, 0), cA + kstep, voffA); PG8_STAGE(PG8_SB(1, 1), cB + hstep + kstep, voffB);
;         PG8_WAIT_V(6); PG8_BAR;
.LBB0_980:
	s_mov_b64 s[4:5], 0x80
	s_and_b32 s22, s18, 3
	s_add_i32 m0, s11, 0x18000
	v_lshl_add_u64 v[16:17], v[16:17], 0, s[4:5]
	s_lshl_b32 s17, s16, 13
	s_lshl_b32 s26, s22, 12
	s_waitcnt vmcnt(2)
	s_barrier
	global_load_lds_dwordx4 v[16:17], off
	v_lshl_add_u64 v[14:15], v[14:15], 0, s[4:5]
	s_add_i32 m0, s11, 0x1a000
	s_add_i32 s24, s11, 0x8000
	s_add_i32 s25, s11, 0xa000
	global_load_lds_dwordx4 v[14:15], off
	v_lshl_add_u64 v[12:13], v[12:13], 0, s[4:5]
	s_mov_b32 m0, s24
	s_add_u32 s28, s0, 0x40080
	global_load_lds_dwordx4 v[12:13], off
	v_lshl_add_u64 v[10:11], v[10:11], 0, s[4:5]
	s_mov_b32 m0, s25
	s_addc_u32 s29, s1, 0
	global_load_lds_dwordx4 v[10:11], off
	s_add_i32 m0, s11, 0x1c000
	v_lshl_add_u64 v[10:11], s[28:29], 0, v[6:7]
	global_load_lds_dwordx4 v[10:11], off
	v_lshl_add_u64 v[10:11], s[28:29], 0, v[2:3]
	s_add_i32 m0, s11, 0x1e000
	v_lshl_or_b32 v149, s16, 6, v1
	global_load_lds_dwordx4 v[10:11], off
	v_and_b32_e32 v10, 48, v0
	v_lshl_or_b32 v11, v1, 6, v10
	v_lshlrev_b32_e32 v1, 2, v1
	v_and_b32_e32 v1, 32, v1
	v_bitop3_b32 v13, v11, s17, v1 bitop3:0xde
	v_lshlrev_b32_e32 v1, 6, v0
	s_movk_i32 s16, 0x3c0
	v_and_or_b32 v1, v1, s16, v10
	v_lshlrev_b32_e32 v10, 2, v0
	v_and_b32_e32 v10, 32, v10
	v_bitop3_b32 v12, s26, v1, v10 bitop3:0xf6
	s_add_u32 s26, s6, 0xe000100
	v_lshlrev_b32_e32 v0, 8, v0
	v_lshlrev_b32_e32 v11, 4, v146
	s_addc_u32 s27, s7, 0
	v_and_b32_e32 v0, 0x18000, v0
	v_lshlrev_b32_e32 v10, 11, v150
	v_and_b32_e32 v11, 0x38000, v11
	v_or3_b32 v0, v147, v0, v10
	v_or3_b32 v10, v147, v11, v10
	s_add_u32 s28, s15, 0xa00100
	s_waitcnt vmcnt(6)
	v_add_u32_e32 v0, v0, v148
	v_mov_b32_e32 v1, v7
	v_add_u32_e32 v10, v10, v148
	v_mov_b32_e32 v11, v7
	s_addc_u32 s29, 0, 0
	s_add_i32 s35, 0, 0x10000
	s_add_i32 s36, 0, 0x14000
	s_add_i32 s47, 0, 0x18000
	s_add_i32 s48, 0, 0x1c000
	v_lshl_add_u64 v[0:1], s[6:7], 0, v[0:1]
	s_mov_b64 s[16:17], 0xe040080
	v_lshl_add_u64 v[10:11], s[6:7], 0, v[10:11]
	s_add_i32 s39, s35, s14
	s_add_i32 s45, s36, s14
	s_add_i32 s49, s47, s14
	s_add_i32 s51, s48, s14
	v_lshl_add_u64 v[0:1], v[0:1], 0, s[16:17]
	v_lshl_add_u64 v[10:11], v[10:11], 0, s[16:17]
	s_mov_b32 s34, -2
	v_add_u32_e32 v13, 0, v13
	s_add_i32 s37, s11, 0xc000
	s_add_i32 s38, s11, 0xe000
	s_add_i32 s44, s39, 0x2000
	s_add_i32 s46, s45, 0x2000
	s_add_i32 s50, s49, 0x2000
	s_add_i32 s52, s51, 0x2000
	s_mov_b64 s[6:7], 0x100
	s_barrier
	s_waitcnt vmcnt(0)
	.p2align 6
